# P0 transposition: per-wave row rotation spread so every XCD covers all 32 row pairs
# speedup vs baseline: 1.0107x; 1.0044x over previous
; #define LAS __attribute__((address_space(3)))
; __device__ __forceinline__ void transpose_item(const float* W, int K, int N, bf16* WT, int mode, LAS float* scr, int item, int lane) {
;     const int nblk = N / 32, kb = item / nblk, nb = item % nblk, k0 = 64 * kb, n0 = 32 * nb;
;     const int drow0 = (mode == 0) ? n0 : (mode == 3) ? ((n0 < 2048) ? 256 * (n0 >> 8) + 128 * ((n0 >> 5) & 1) + 32 * ((n0 >> 6) & 3) : n0)
;                                               : (256 * (n0 >> 7) + (n0 & 127) + (mode == 2 ? 128 : 0));
; #pragma unroll 8
;     for (int i = 0; i < 32; ++i) { const int kk = 2 * i + (lane >> 5); scr[kk * 33 + (lane & 31)] = W[(size_t)(k0 + kk) * N + n0 + (lane & 31)]; }
;     asm volatile("s_waitcnt lgkmcnt(0)" ::: "memory");
.Lp0_mdone:
	s_lshl_b32 s29, s19, 6
	s_mul_i32 s12, s29, s2
	s_add_i32 s12, s12, s18
	s_lshl_b32 s12, s12, 2
	s_add_u32 s36, s44, s12
	s_addc_u32 s37, s45, 0
	v_mul_u32_u24_e32 v16, s2, v0
	s_lshl_b32 s13, s2, 3
	v_lshl_add_u32 v16, v16, 2, v2
	v_mov_b32_e32 v11, s13
	s_and_b32 s24, s26, 7
	s_lshl_b32 s24, s24, 2
	s_bfe_u32 s12, s26, 0x20006
	s_or_b32 s24, s24, s12
	s_cmp_eq_u32 s30, 0
	s_cbranch_scc1 .Lp0_np1
	s_waitcnt vmcnt(0)
	s_mul_i32 s13, s46, 264
	v_add_u32_e32 v54, s13, v10
	ds_write_b32 v54, v22
	s_add_i32 s12, s46, 1
	s_and_b32 s12, s12, 31
	s_mul_i32 s13, s12, 264
	v_add_u32_e32 v55, s13, v10
	ds_write_b32 v55, v23
	s_add_i32 s12, s46, 2
	s_and_b32 s12, s12, 31
	s_mul_i32 s13, s12, 264
	v_add_u32_e32 v56, s13, v10
	ds_write_b32 v56, v24
	s_add_i32 s12, s46, 3
	s_and_b32 s12, s12, 31
	s_mul_i32 s13, s12, 264
	v_add_u32_e32 v57, s13, v10
	ds_write_b32 v57, v25
	s_add_i32 s12, s46, 4
	s_and_b32 s12, s12, 31
	s_mul_i32 s13, s12, 264
	v_add_u32_e32 v58, s13, v10
	ds_write_b32 v58, v26
	s_add_i32 s12, s46, 5
	s_and_b32 s12, s12, 31
	s_mul_i32 s13, s12, 264
	v_add_u32_e32 v59, s13, v10
	ds_write_b32 v59, v27
	s_add_i32 s12, s46, 6
	s_and_b32 s12, s12, 31
	s_mul_i32 s13, s12, 264
	v_add_u32_e32 v60, s13, v10
	ds_write_b32 v60, v28
	s_add_i32 s12, s46, 7
	s_and_b32 s12, s12, 31
	s_mul_i32 s13, s12, 264
	v_add_u32_e32 v61, s13, v10
	ds_write_b32 v61, v29
	s_add_i32 s12, s46, 8
	s_and_b32 s12, s12, 31
	s_mul_i32 s13, s12, 264
	v_add_u32_e32 v54, s13, v10
	ds_write_b32 v54, v30
	s_add_i32 s12, s46, 9
	s_and_b32 s12, s12, 31
	s_mul_i32 s13, s12, 264
	v_add_u32_e32 v55, s13, v10
	ds_write_b32 v55, v31
	s_add_i32 s12, s46, 10
	s_and_b32 s12, s12, 31
	s_mul_i32 s13, s12, 264
	v_add_u32_e32 v56, s13, v10
	ds_write_b32 v56, v32
	s_add_i32 s12, s46, 11
	s_and_b32 s12, s12, 31
	s_mul_i32 s13, s12, 264
	v_add_u32_e32 v57, s13, v10
	ds_write_b32 v57, v33
	s_add_i32 s12, s46, 12
	s_and_b32 s12, s12, 31
	s_mul_i32 s13, s12, 264
	v_add_u32_e32 v58, s13, v10
	ds_write_b32 v58, v34
	s_add_i32 s12, s46, 13
	s_and_b32 s12, s12, 31
	s_mul_i32 s13, s12, 264
	v_add_u32_e32 v59, s13, v10
	ds_write_b32 v59, v35
	s_add_i32 s12, s46, 14
	s_and_b32 s12, s12, 31
	s_mul_i32 s13, s12, 264
	v_add_u32_e32 v60, s13, v10
	ds_write_b32 v60, v36
	s_add_i32 s12, s46, 15
	s_and_b32 s12, s12, 31
	s_mul_i32 s13, s12, 264
	v_add_u32_e32 v61, s13, v10
	ds_write_b32 v61, v37
	s_add_i32 s12, s46, 16
	s_and_b32 s12, s12, 31
	s_mul_i32 s13, s12, 264
	v_add_u32_e32 v54, s13, v10
	ds_write_b32 v54, v38
	s_add_i32 s12, s46, 17
	s_and_b32 s12, s12, 31
	s_mul_i32 s13, s12, 264
	v_add_u32_e32 v55, s13, v10
	ds_write_b32 v55, v39
	s_add_i32 s12, s46, 18
	s_and_b32 s12, s12, 31
	s_mul_i32 s13, s12, 264
	v_add_u32_e32 v56, s13, v10
	ds_write_b32 v56, v40
	s_add_i32 s12, s46, 19
	s_and_b32 s12, s12, 31
	s_mul_i32 s13, s12, 264
	v_add_u32_e32 v57, s13, v10
	ds_write_b32 v57, v41
	s_add_i32 s12, s46, 20
	s_and_b32 s12, s12, 31
	s_mul_i32 s13, s12, 264
	v_add_u32_e32 v58, s13, v10
	ds_write_b32 v58, v42
	s_add_i32 s12, s46, 21
	s_and_b32 s12, s12, 31
	s_mul_i32 s13, s12, 264
	v_add_u32_e32 v59, s13, v10
	ds_write_b32 v59, v43
	s_add_i32 s12, s46, 22
	s_and_b32 s12, s12, 31
	s_mul_i32 s13, s12, 264
	v_add_u32_e32 v60, s13, v10
	ds_write_b32 v60, v44
	s_add_i32 s12, s46, 23
	s_and_b32 s12, s12, 31
	s_mul_i32 s13, s12, 264
	v_add_u32_e32 v61, s13, v10
	ds_write_b32 v61, v45
	s_add_i32 s12, s46, 24
	s_and_b32 s12, s12, 31
	s_mul_i32 s13, s12, 264
	v_add_u32_e32 v54, s13, v10
	ds_write_b32 v54, v46
	s_add_i32 s12, s46, 25
	s_and_b32 s12, s12, 31
	s_mul_i32 s13, s12, 264
	v_add_u32_e32 v55, s13, v10
	ds_write_b32 v55, v47
	s_add_i32 s12, s46, 26
	s_and_b32 s12, s12, 31
	s_mul_i32 s13, s12, 264
	v_add_u32_e32 v56, s13, v10
	ds_write_b32 v56, v48
	s_add_i32 s12, s46, 27
	s_and_b32 s12, s12, 31
	s_mul_i32 s13, s12, 264
	v_add_u32_e32 v57, s13, v10
	ds_write_b32 v57, v49
	s_add_i32 s12, s46, 28
	s_and_b32 s12, s12, 31
	s_mul_i32 s13, s12, 264
	v_add_u32_e32 v58, s13, v10
	ds_write_b32 v58, v50
	s_add_i32 s12, s46, 29
	s_and_b32 s12, s12, 31
	s_mul_i32 s13, s12, 264
	v_add_u32_e32 v59, s13, v10
	ds_write_b32 v59, v51
	s_add_i32 s12, s46, 30
	s_and_b32 s12, s12, 31
	s_mul_i32 s13, s12, 264
	v_add_u32_e32 v60, s13, v10
	ds_write_b32 v60, v52
	s_add_i32 s12, s46, 31
	s_and_b32 s12, s12, 31
	s_mul_i32 s13, s12, 264
	v_add_u32_e32 v61, s13, v10
	ds_write_b32 v61, v53
